# v7 + EpiRes epilogues prefetch the residual lines of row groups 1..7 into L2 at the top of the epilogue
# speedup vs baseline: 1.0084x; 1.0084x over previous
.LBB0_983:
	v_lshl_add_u32 v146, s28, 8, v148
	v_ashrrev_i32_e32 v147, 31, v146
	v_lshl_or_b32 v144, s30, 8, v150
	v_lshlrev_b64 v[156:157], 11, v[146:147]
	v_ashrrev_i32_e32 v145, 31, v144
	v_lshl_add_u64 v[156:157], s[14:15], 0, v[156:157]
	v_lshl_add_u64 v[166:167], v[144:145], 1, v[156:157]
	v_mov_b32_e32 v212, 0x8000
	v_mov_b32_e32 v213, 0
	v_mov_b32_e32 v210, 0x28000
	v_mov_b32_e32 v211, 0
	v_lshl_add_u64 v[214:215], v[166:167], 0, v[212:213]
	global_load_dword v196, v[214:215], off
	global_load_dword v197, v[214:215], off offset:256
	v_lshl_add_u64 v[214:215], v[214:215], 0, v[212:213]
	global_load_dword v198, v[214:215], off
	global_load_dword v199, v[214:215], off offset:256
	v_lshl_add_u64 v[214:215], v[214:215], 0, v[212:213]
	global_load_dword v200, v[214:215], off
	global_load_dword v201, v[214:215], off offset:256
	v_lshl_add_u64 v[214:215], v[214:215], 0, v[210:211]
	global_load_dword v202, v[214:215], off
	global_load_dword v203, v[214:215], off offset:256
	v_lshl_add_u64 v[214:215], v[214:215], 0, v[212:213]
	global_load_dword v204, v[214:215], off
	global_load_dword v205, v[214:215], off offset:256
	v_lshl_add_u64 v[214:215], v[214:215], 0, v[212:213]
	global_load_dword v206, v[214:215], off
	global_load_dword v207, v[214:215], off offset:256
	v_lshl_add_u64 v[214:215], v[214:215], 0, v[212:213]
	global_load_dword v208, v[214:215], off
	global_load_dword v209, v[214:215], off offset:256
	flat_load_dwordx4 v[158:161], v[166:167]
	flat_load_dwordx4 v[162:165], v[166:167] offset:256
	v_and_b32_e32 v156, 64, v154
	v_xor_b32_e32 v155, 16, v154
	v_add_u32_e32 v156, 64, v156
	v_xor_b32_e32 v157, 32, v154
	v_cmp_lt_i32_e32 vcc, v155, v156
	s_waitcnt vmcnt(0) lgkmcnt(0)
	v_lshlrev_b32_e32 v168, 16, v158
	v_cndmask_b32_e32 v155, v154, v155, vcc
	v_cmp_lt_i32_e32 vcc, v157, v156
	v_and_b32_e32 v169, 0xffff0000, v158
	v_lshlrev_b32_e32 v158, 16, v159
	v_and_b32_e32 v159, 0xffff0000, v159
	v_lshlrev_b32_e32 v170, 16, v160
	v_and_b32_e32 v171, 0xffff0000, v160
	v_lshlrev_b32_e32 v160, 16, v161
	v_and_b32_e32 v161, 0xffff0000, v161
	v_lshlrev_b32_e32 v172, 16, v162
	v_and_b32_e32 v173, 0xffff0000, v162
	v_lshlrev_b32_e32 v162, 16, v163
	v_and_b32_e32 v163, 0xffff0000, v163
	v_lshlrev_b32_e32 v174, 16, v164
	v_and_b32_e32 v175, 0xffff0000, v164
	v_lshlrev_b32_e32 v164, 16, v165
	v_and_b32_e32 v165, 0xffff0000, v165
	v_cndmask_b32_e32 v157, v154, v157, vcc
	v_pk_add_f32 v[126:127], v[126:127], v[158:159]
	v_pk_add_f32 v[124:125], v[124:125], v[168:169]
	v_pk_add_f32 v[122:123], v[122:123], v[160:161]
	v_pk_add_f32 v[120:121], v[120:121], v[170:171]
	v_pk_add_f32 v[118:119], v[118:119], v[162:163]
	v_pk_add_f32 v[116:117], v[116:117], v[172:173]
	v_pk_add_f32 v[158:159], v[114:115], v[164:165]
	v_pk_add_f32 v[160:161], v[112:113], v[174:175]
	v_lshlrev_b32_e32 v156, 2, v155
	v_lshlrev_b32_e32 v155, 2, v157
	v_cvt_pk_bf16_f32 v112, v124, v125
	v_cvt_pk_bf16_f32 v113, v126, v127
	v_mul_f32_e32 v114, v125, v125
	v_mul_f32_e32 v115, v127, v127
	v_mul_f32_e32 v125, v121, v121
	v_mul_f32_e32 v127, v123, v123
	v_mul_f32_e32 v157, v117, v117
	v_mul_f32_e32 v162, v119, v119
	v_mul_f32_e32 v163, v161, v161
	v_mul_f32_e32 v164, v159, v159
	v_fmac_f32_e32 v114, v124, v124
	v_fmac_f32_e32 v115, v126, v126
	v_fmac_f32_e32 v125, v120, v120
	v_fmac_f32_e32 v127, v122, v122
	v_fmac_f32_e32 v157, v116, v116
	v_fmac_f32_e32 v162, v118, v118
	v_fmac_f32_e32 v163, v160, v160
	v_fmac_f32_e32 v164, v158, v158
	v_add_f32_e32 v114, v114, v115
	v_add_f32_e32 v115, v125, v127
	v_add_f32_e32 v124, v157, v162
	v_add_f32_e32 v125, v163, v164
	v_add_f32_e32 v114, v114, v115
	v_add_f32_e32 v115, v124, v125
	v_add_f32_e32 v124, v114, v115
	ds_bpermute_b32 v125, v156, v124
	v_cvt_pk_bf16_f32 v114, v120, v121
	v_cvt_pk_bf16_f32 v115, v122, v123
	flat_store_dwordx4 v[166:167], v[112:115]
	s_waitcnt lgkmcnt(0)
	s_nop 0
	v_add_f32_e32 v112, v124, v125
	ds_bpermute_b32 v113, v155, v112
	v_cvt_pk_bf16_f32 v114, v116, v117
	v_cvt_pk_bf16_f32 v115, v118, v119
	v_cvt_pk_bf16_f32 v116, v160, v161
	v_cvt_pk_bf16_f32 v117, v158, v159
	flat_store_dwordx4 v[166:167], v[114:117] offset:256
	s_and_saveexec_b64 s[28:29], s[4:5]
	s_cbranch_execz .LBB0_985
	v_lshl_add_u64 v[114:115], v[146:147], 2, s[12:13]
	s_waitcnt lgkmcnt(0)
	v_add_f32_e32 v112, v112, v113
	flat_atomic_add_f32 v[114:115], v112

.LBB0_1153:
	v_lshl_add_u32 v146, s38, 8, v148
	v_lshl_or_b32 v144, s36, 8, v150
	v_ashrrev_i32_e32 v147, 31, v146
	v_ashrrev_i32_e32 v145, 31, v144
	v_lshlrev_b64 v[156:157], 10, v[146:147]
	v_lshl_add_u64 v[156:157], v[156:157], 0, v[144:145]
	v_lshlrev_b64 v[160:161], 1, v[156:157]
	v_lshl_add_u64 v[156:157], s[16:17], 0, v[160:161]
	v_mov_b32_e32 v212, 0x8000
	v_mov_b32_e32 v213, 0
	v_mov_b32_e32 v210, 0x28000
	v_mov_b32_e32 v211, 0
	v_lshl_add_u64 v[214:215], v[156:157], 0, v[212:213]
	global_load_dword v196, v[214:215], off
	global_load_dword v197, v[214:215], off offset:256
	v_lshl_add_u64 v[214:215], v[214:215], 0, v[212:213]
	global_load_dword v198, v[214:215], off
	global_load_dword v199, v[214:215], off offset:256
	v_lshl_add_u64 v[214:215], v[214:215], 0, v[212:213]
	global_load_dword v200, v[214:215], off
	global_load_dword v201, v[214:215], off offset:256
	v_lshl_add_u64 v[214:215], v[214:215], 0, v[210:211]
	global_load_dword v202, v[214:215], off
	global_load_dword v203, v[214:215], off offset:256
	v_lshl_add_u64 v[214:215], v[214:215], 0, v[212:213]
	global_load_dword v204, v[214:215], off
	global_load_dword v205, v[214:215], off offset:256
	v_lshl_add_u64 v[214:215], v[214:215], 0, v[212:213]
	global_load_dword v206, v[214:215], off
	global_load_dword v207, v[214:215], off offset:256
	v_lshl_add_u64 v[214:215], v[214:215], 0, v[212:213]
	global_load_dword v208, v[214:215], off
	global_load_dword v209, v[214:215], off offset:256
	flat_load_dwordx4 v[156:159], v[156:157]
	v_lshl_add_u64 v[162:163], s[50:51], 0, v[160:161]
	v_or_b32_e32 v160, 0x100, v160
	v_lshl_add_u64 v[160:161], s[16:17], 0, v[160:161]
	v_xor_b32_e32 v155, 32, v154
	s_waitcnt vmcnt(0) lgkmcnt(0)
	v_lshlrev_b32_e32 v164, 16, v156
	v_and_b32_e32 v165, 0xffff0000, v156
	v_lshlrev_b32_e32 v156, 16, v157
	v_and_b32_e32 v157, 0xffff0000, v157
	v_lshlrev_b32_e32 v166, 16, v158
	v_and_b32_e32 v167, 0xffff0000, v158
	v_lshlrev_b32_e32 v158, 16, v159
	v_and_b32_e32 v159, 0xffff0000, v159
	v_pk_add_f32 v[126:127], v[126:127], v[156:157]
	v_pk_add_f32 v[156:157], v[124:125], v[164:165]
	v_pk_add_f32 v[158:159], v[122:123], v[158:159]
	v_pk_add_f32 v[164:165], v[120:121], v[166:167]
	v_cvt_pk_bf16_f32 v120, v156, v157
	v_cvt_pk_bf16_f32 v121, v126, v127
	v_cvt_pk_bf16_f32 v122, v164, v165
	v_cvt_pk_bf16_f32 v123, v158, v159
	global_store_dwordx4 v[162:163], v[120:123], off
	flat_load_dwordx4 v[122:125], v[160:161]
	v_mul_f32_e32 v157, v157, v157
	v_mul_f32_e32 v127, v127, v127
	v_mul_f32_e32 v160, v165, v165
	v_mul_f32_e32 v159, v159, v159
	v_fmac_f32_e32 v157, v156, v156
	v_fmac_f32_e32 v127, v126, v126
	v_fmac_f32_e32 v160, v164, v164
	v_fmac_f32_e32 v159, v158, v158
	v_add_f32_e32 v126, v157, v127
	v_add_f32_e32 v127, v160, v159
	v_add_f32_e32 v158, v126, v127
	v_and_b32_e32 v121, 64, v154
	v_xor_b32_e32 v120, 16, v154
	v_add_u32_e32 v121, 64, v121
	v_cmp_lt_i32_e32 vcc, v120, v121
	s_waitcnt vmcnt(0) lgkmcnt(0)
	v_lshlrev_b32_e32 v126, 16, v122
	v_and_b32_e32 v127, 0xffff0000, v122
	v_lshlrev_b32_e32 v122, 16, v123
	v_and_b32_e32 v123, 0xffff0000, v123
	v_lshlrev_b32_e32 v156, 16, v124
	v_and_b32_e32 v157, 0xffff0000, v124
	v_lshlrev_b32_e32 v124, 16, v125
	v_and_b32_e32 v125, 0xffff0000, v125
	v_pk_add_f32 v[118:119], v[118:119], v[122:123]
	v_pk_add_f32 v[116:117], v[116:117], v[126:127]
	v_pk_add_f32 v[122:123], v[114:115], v[124:125]
	v_pk_add_f32 v[124:125], v[112:113], v[156:157]
	v_mul_f32_e32 v112, v117, v117
	v_mul_f32_e32 v113, v119, v119
	v_mul_f32_e32 v114, v125, v125
	v_mul_f32_e32 v115, v123, v123
	v_fmac_f32_e32 v112, v116, v116
	v_fmac_f32_e32 v113, v118, v118
	v_fmac_f32_e32 v114, v124, v124
	v_fmac_f32_e32 v115, v122, v122
	v_add_f32_e32 v112, v112, v113
	v_add_f32_e32 v113, v114, v115
	v_cndmask_b32_e32 v120, v154, v120, vcc
	v_add_f32_e32 v112, v112, v113
	v_lshlrev_b32_e32 v120, 2, v120
	v_add_f32_e32 v112, v158, v112
	ds_bpermute_b32 v113, v120, v112
	v_cmp_lt_i32_e32 vcc, v155, v121
	v_cvt_pk_bf16_f32 v116, v116, v117
	v_cvt_pk_bf16_f32 v117, v118, v119
	v_cndmask_b32_e32 v114, v154, v155, vcc
	v_lshlrev_b32_e32 v114, 2, v114
	s_waitcnt lgkmcnt(0)
	v_add_f32_e32 v112, v112, v113
	ds_bpermute_b32 v113, v114, v112
	v_cvt_pk_bf16_f32 v118, v124, v125
	v_cvt_pk_bf16_f32 v119, v122, v123
	global_store_dwordx4 v[162:163], v[116:119], off offset:256
	s_and_saveexec_b64 s[36:37], s[4:5]
	s_cbranch_execz .LBB0_1155
	v_lshl_add_u64 v[116:117], v[146:147], 2, s[14:15]
	s_waitcnt lgkmcnt(0)
	v_add_f32_e32 v112, v112, v113
	flat_atomic_add_f32 v[116:117], v112

.LBB0_1616:
	v_lshl_add_u32 v146, s56, 8, v148
	v_lshl_or_b32 v144, s26, 8, v150
	v_ashrrev_i32_e32 v147, 31, v146
	v_ashrrev_i32_e32 v145, 31, v144
	v_lshlrev_b64 v[154:155], 10, v[146:147]
	v_lshl_add_u64 v[154:155], v[154:155], 0, v[144:145]
	v_lshlrev_b64 v[158:159], 1, v[154:155]
	v_lshl_add_u64 v[160:161], s[50:51], 0, v[158:159]
	v_mov_b32_e32 v210, 0x8000
	v_mov_b32_e32 v211, 0
	v_mov_b32_e32 v208, 0x28000
	v_mov_b32_e32 v209, 0
	v_lshl_add_u64 v[212:213], v[160:161], 0, v[210:211]
	global_load_dword v194, v[212:213], off
	global_load_dword v195, v[212:213], off offset:256
	v_lshl_add_u64 v[212:213], v[212:213], 0, v[210:211]
	global_load_dword v196, v[212:213], off
	global_load_dword v197, v[212:213], off offset:256
	v_lshl_add_u64 v[212:213], v[212:213], 0, v[210:211]
	global_load_dword v198, v[212:213], off
	global_load_dword v199, v[212:213], off offset:256
	v_lshl_add_u64 v[212:213], v[212:213], 0, v[208:209]
	global_load_dword v200, v[212:213], off
	global_load_dword v201, v[212:213], off offset:256
	v_lshl_add_u64 v[212:213], v[212:213], 0, v[210:211]
	global_load_dword v202, v[212:213], off
	global_load_dword v203, v[212:213], off offset:256
	v_lshl_add_u64 v[212:213], v[212:213], 0, v[210:211]
	global_load_dword v204, v[212:213], off
	global_load_dword v205, v[212:213], off offset:256
	v_lshl_add_u64 v[212:213], v[212:213], 0, v[210:211]
	global_load_dword v206, v[212:213], off
	global_load_dword v207, v[212:213], off offset:256
	global_load_dwordx4 v[154:157], v[160:161], off
	v_lshl_add_u64 v[158:159], s[8:9], 0, v[158:159]
	v_xor_b32_e32 v153, 32, v152
	s_waitcnt vmcnt(0)
	v_lshlrev_b32_e32 v162, 16, v154
	v_and_b32_e32 v163, 0xffff0000, v154
	v_lshlrev_b32_e32 v154, 16, v155
	v_and_b32_e32 v155, 0xffff0000, v155
	v_lshlrev_b32_e32 v164, 16, v156
	v_and_b32_e32 v165, 0xffff0000, v156
	v_lshlrev_b32_e32 v156, 16, v157
	v_and_b32_e32 v157, 0xffff0000, v157
	v_pk_add_f32 v[126:127], v[126:127], v[154:155]
	v_pk_add_f32 v[154:155], v[124:125], v[162:163]
	v_pk_add_f32 v[156:157], v[122:123], v[156:157]
	v_pk_add_f32 v[162:163], v[120:121], v[164:165]
	v_cvt_pk_bf16_f32 v120, v154, v155
	v_cvt_pk_bf16_f32 v121, v126, v127
	v_cvt_pk_bf16_f32 v122, v162, v163
	v_cvt_pk_bf16_f32 v123, v156, v157
	flat_store_dwordx4 v[158:159], v[120:123]
	global_load_dwordx4 v[122:125], v[160:161], off offset:256
	v_mul_f32_e32 v155, v155, v155
	v_mul_f32_e32 v127, v127, v127
	v_mul_f32_e32 v160, v163, v163
	v_mul_f32_e32 v157, v157, v157
	v_fmac_f32_e32 v155, v154, v154
	v_fmac_f32_e32 v127, v126, v126
	v_fmac_f32_e32 v160, v162, v162
	v_fmac_f32_e32 v157, v156, v156
	v_add_f32_e32 v126, v155, v127
	v_add_f32_e32 v127, v160, v157
	v_add_f32_e32 v156, v126, v127
	v_and_b32_e32 v121, 64, v152
	v_xor_b32_e32 v120, 16, v152
	v_add_u32_e32 v121, 64, v121
	v_cmp_lt_i32_e32 vcc, v120, v121
	s_waitcnt vmcnt(0)
	v_lshlrev_b32_e32 v126, 16, v122
	v_and_b32_e32 v127, 0xffff0000, v122
	v_lshlrev_b32_e32 v122, 16, v123
	v_and_b32_e32 v123, 0xffff0000, v123
	v_lshlrev_b32_e32 v154, 16, v124
	v_and_b32_e32 v155, 0xffff0000, v124
	v_lshlrev_b32_e32 v124, 16, v125
	v_and_b32_e32 v125, 0xffff0000, v125
	v_pk_add_f32 v[118:119], v[118:119], v[122:123]
	v_pk_add_f32 v[116:117], v[116:117], v[126:127]
	v_pk_add_f32 v[122:123], v[114:115], v[124:125]
	v_pk_add_f32 v[124:125], v[112:113], v[154:155]
	v_mul_f32_e32 v112, v117, v117
	v_mul_f32_e32 v113, v119, v119
	v_mul_f32_e32 v114, v125, v125
	v_mul_f32_e32 v115, v123, v123
	v_fmac_f32_e32 v112, v116, v116
	v_fmac_f32_e32 v113, v118, v118
	v_fmac_f32_e32 v114, v124, v124
	v_fmac_f32_e32 v115, v122, v122
	v_add_f32_e32 v112, v112, v113
	v_add_f32_e32 v113, v114, v115
	v_cndmask_b32_e32 v120, v152, v120, vcc
	v_add_f32_e32 v112, v112, v113
	v_lshlrev_b32_e32 v120, 2, v120
	v_add_f32_e32 v112, v156, v112
	ds_bpermute_b32 v113, v120, v112
	v_cmp_lt_i32_e32 vcc, v153, v121
	v_cvt_pk_bf16_f32 v116, v116, v117
	v_cvt_pk_bf16_f32 v117, v118, v119
	v_cndmask_b32_e32 v114, v152, v153, vcc
	v_lshlrev_b32_e32 v114, 2, v114
	s_waitcnt lgkmcnt(0)
	v_add_f32_e32 v112, v112, v113
	ds_bpermute_b32 v113, v114, v112
	v_cvt_pk_bf16_f32 v118, v124, v125
	v_cvt_pk_bf16_f32 v119, v122, v123
	flat_store_dwordx4 v[158:159], v[116:119] offset:256
	s_and_saveexec_b64 s[6:7], s[0:1]
	s_cbranch_execz .LBB0_1618
	v_lshl_add_u64 v[116:117], v[146:147], 2, s[14:15]
	s_waitcnt lgkmcnt(0)
	v_add_f32_e32 v112, v112, v113
	flat_atomic_add_f32 v[116:117], v112

.LBB0_1786:
	v_lshl_add_u32 v146, s26, 8, v148
	v_ashrrev_i32_e32 v147, 31, v146
	v_lshl_or_b32 v144, s24, 8, v150
	v_lshlrev_b64 v[156:157], 11, v[146:147]
	v_ashrrev_i32_e32 v145, 31, v144
	v_lshl_add_u64 v[156:157], s[6:7], 0, v[156:157]
	v_lshl_add_u64 v[166:167], v[144:145], 1, v[156:157]
	v_mov_b32_e32 v212, 0x8000
	v_mov_b32_e32 v213, 0
	v_mov_b32_e32 v210, 0x28000
	v_mov_b32_e32 v211, 0
	v_lshl_add_u64 v[214:215], v[166:167], 0, v[212:213]
	global_load_dword v196, v[214:215], off
	global_load_dword v197, v[214:215], off offset:256
	v_lshl_add_u64 v[214:215], v[214:215], 0, v[212:213]
	global_load_dword v198, v[214:215], off
	global_load_dword v199, v[214:215], off offset:256
	v_lshl_add_u64 v[214:215], v[214:215], 0, v[212:213]
	global_load_dword v200, v[214:215], off
	global_load_dword v201, v[214:215], off offset:256
	v_lshl_add_u64 v[214:215], v[214:215], 0, v[210:211]
	global_load_dword v202, v[214:215], off
	global_load_dword v203, v[214:215], off offset:256
	v_lshl_add_u64 v[214:215], v[214:215], 0, v[212:213]
	global_load_dword v204, v[214:215], off
	global_load_dword v205, v[214:215], off offset:256
	v_lshl_add_u64 v[214:215], v[214:215], 0, v[212:213]
	global_load_dword v206, v[214:215], off
	global_load_dword v207, v[214:215], off offset:256
	v_lshl_add_u64 v[214:215], v[214:215], 0, v[212:213]
	global_load_dword v208, v[214:215], off
	global_load_dword v209, v[214:215], off offset:256
	flat_load_dwordx4 v[158:161], v[166:167]
	flat_load_dwordx4 v[162:165], v[166:167] offset:256
	v_and_b32_e32 v156, 64, v154
	v_xor_b32_e32 v155, 16, v154
	v_add_u32_e32 v156, 64, v156
	v_xor_b32_e32 v157, 32, v154
	v_cmp_lt_i32_e32 vcc, v155, v156
	s_waitcnt vmcnt(0) lgkmcnt(0)
	v_lshlrev_b32_e32 v168, 16, v158
	v_cndmask_b32_e32 v155, v154, v155, vcc
	v_cmp_lt_i32_e32 vcc, v157, v156
	v_and_b32_e32 v169, 0xffff0000, v158
	v_lshlrev_b32_e32 v158, 16, v159
	v_and_b32_e32 v159, 0xffff0000, v159
	v_lshlrev_b32_e32 v170, 16, v160
	v_and_b32_e32 v171, 0xffff0000, v160
	v_lshlrev_b32_e32 v160, 16, v161
	v_and_b32_e32 v161, 0xffff0000, v161
	v_lshlrev_b32_e32 v172, 16, v162
	v_and_b32_e32 v173, 0xffff0000, v162
	v_lshlrev_b32_e32 v162, 16, v163
	v_and_b32_e32 v163, 0xffff0000, v163
	v_lshlrev_b32_e32 v174, 16, v164
	v_and_b32_e32 v175, 0xffff0000, v164
	v_lshlrev_b32_e32 v164, 16, v165
	v_and_b32_e32 v165, 0xffff0000, v165
	v_cndmask_b32_e32 v157, v154, v157, vcc
	v_pk_add_f32 v[126:127], v[126:127], v[158:159]
	v_pk_add_f32 v[124:125], v[124:125], v[168:169]
	v_pk_add_f32 v[122:123], v[122:123], v[160:161]
	v_pk_add_f32 v[120:121], v[120:121], v[170:171]
	v_pk_add_f32 v[118:119], v[118:119], v[162:163]
	v_pk_add_f32 v[116:117], v[116:117], v[172:173]
	v_pk_add_f32 v[158:159], v[114:115], v[164:165]
	v_pk_add_f32 v[160:161], v[112:113], v[174:175]
	v_lshlrev_b32_e32 v156, 2, v155
	v_lshlrev_b32_e32 v155, 2, v157
	v_cvt_pk_bf16_f32 v112, v124, v125
	v_cvt_pk_bf16_f32 v113, v126, v127
	v_mul_f32_e32 v114, v125, v125
	v_mul_f32_e32 v115, v127, v127
	v_mul_f32_e32 v125, v121, v121
	v_mul_f32_e32 v127, v123, v123
	v_mul_f32_e32 v157, v117, v117
	v_mul_f32_e32 v162, v119, v119
	v_mul_f32_e32 v163, v161, v161
	v_mul_f32_e32 v164, v159, v159
	v_fmac_f32_e32 v114, v124, v124
	v_fmac_f32_e32 v115, v126, v126
	v_fmac_f32_e32 v125, v120, v120
	v_fmac_f32_e32 v127, v122, v122
	v_fmac_f32_e32 v157, v116, v116
	v_fmac_f32_e32 v162, v118, v118
	v_fmac_f32_e32 v163, v160, v160
	v_fmac_f32_e32 v164, v158, v158
	v_add_f32_e32 v114, v114, v115
	v_add_f32_e32 v115, v125, v127
	v_add_f32_e32 v124, v157, v162
	v_add_f32_e32 v125, v163, v164
	v_add_f32_e32 v114, v114, v115
	v_add_f32_e32 v115, v124, v125
	v_add_f32_e32 v124, v114, v115
	ds_bpermute_b32 v125, v156, v124
	v_cvt_pk_bf16_f32 v114, v120, v121
	v_cvt_pk_bf16_f32 v115, v122, v123
	flat_store_dwordx4 v[166:167], v[112:115]
	s_waitcnt lgkmcnt(0)
	s_nop 0
	v_add_f32_e32 v112, v124, v125
	ds_bpermute_b32 v113, v155, v112
	v_cvt_pk_bf16_f32 v114, v116, v117
	v_cvt_pk_bf16_f32 v115, v118, v119
	v_cvt_pk_bf16_f32 v116, v160, v161
	v_cvt_pk_bf16_f32 v117, v158, v159
	flat_store_dwordx4 v[166:167], v[114:117] offset:256
	s_and_saveexec_b64 s[24:25], s[0:1]
	s_cbranch_execz .LBB0_1788
	v_lshl_add_u64 v[114:115], v[146:147], 2, s[10:11]
	s_waitcnt lgkmcnt(0)
	v_add_f32_e32 v112, v112, v113
	flat_atomic_add_f32 v[114:115], v112
